# workgroups 160..255 run one decode attention unit (sg = 2*blk, tile-local dependency) during P3's tail; the attention phase skips those 96 units
# speedup vs baseline: 1.0152x; 1.0058x over previous
; __device__ __forceinline__ int fresh_lane() { int l; asm volatile("v_mbcnt_lo_u32_b32 %0, -1, 0\n\tv_mbcnt_hi_u32_b32 %0, -1, %0" : "=v"(l)); return l; }
; #define PG8_BAR __builtin_amdgcn_s_barrier()
; template <class Epi, class Sched, bool ALIGN_EPI = false, bool SP2 = false>
; __device__ __forceinline__ void gemm_phase(PG8_LAS unsigned char* lds, const Gemm g, const Sched& S, const Epi& E, int wave_sgpr) {
;     int tid_ = wave_sgpr * 64 + fresh_lane();
;     const int tid = tid_, wid = __builtin_amdgcn_readfirstlane(tid >> 6), lane = tid & 63, wr = wid >> 2, wc = wid & 3, fr = lane & 15, fq = lane >> 4;
;     const int K = g.K, nt = K / BK;
;     unsigned voffA[2], voffB[2];
; #pragma unroll
;     for (int i = 0; i < 2; ++i) { int R, C; stage_rc(tid * 16 + i * 8192, R, C); const int Rb = Epi::PERM ? ((R & ~31) + perm32(R & 31)) : R;
;         voffA[i] = (unsigned)(R * g.lda + C) * 2u; voffB[i] = (unsigned)(Rb * g.ldb + C) * 2u; }
;     const size_t kstep = (size_t)(BK * 2);
;     const size_t hstepA = (size_t)HALF * g.lda * 2, hstepB = (size_t)HALF * g.ldb * 2;
;     const unsigned ldsw = (unsigned)wid * 1024u;
;     const int aoff = lds_byte(wr * 64 + fr, fq * 8), boff = lds_byte(wc * 32 + fr, fq * 8);
;     ...
;     Unit cur, nxt; int ui = 0;
;     if (!S.next(0, cur)) return;
;     f32x4 acc[2][2][4][2];
; #pragma unroll
;     for (int a = 0; a < 2; ++a)
; #pragma unroll
;         for (int b = 0; b < 2; ++b)
; #pragma unroll
;             for (int m = 0; m < 4; ++m)
; #pragma unroll
;                 for (int n = 0; n < 2; ++n) acc[a][b][m][n] = (f32x4){0.f, 0.f, 0.f, 0.f};
;     bf16x8 At[4][2], B0[2][2], B1[2][2];
;     const char* cA = S.abase(g, cur); const char* cB = S.bbase(g, cur);
;     S.a_ready(cur);
;     if constexpr (SP2) {
;         PG8_STAGE(PG8_SB(0, 0), cB, voffB); PG8_STAGE(PG8_SB(0, 1), cB + hstepB, voffB); PG8_STAGE(PG8_SA(0, 0), cA, voffA); PG8_STAGE(PG8_SA(0, 1), cA + hstepA, voffA);
;         if (wr == 1) PG8_BAR;
;         PG8_WAIT_V(2); PG8_BAR;
;         PG8_STAGE(PG8_SB(1, 0), cB + kstep, voffB); PG8_STAGE(PG8_SA(1, 0), cA + kstep, voffA); PG8_STAGE(PG8_SB(1, 1), cB + hstepB + kstep, voffB);
;         PG8_WAIT_V(6); PG8_BAR;
;     } else {
;         PG8_STAGE(PG8_SB(0, 0), cB, voffB); PG8_STAGE(PG8_SA(0, 0), cA, voffA); PG8_STAGE(PG8_SB(0, 1), cB + hstepB, voffB); PG8_STAGE(PG8_SA(0, 1), cA + hstepA, voffA);
.LBB0_1065:
	s_mov_b32 s101, 0
	v_readlane_b32 s0, v254, 8
	v_readlane_b32 s1, v254, 9
	s_cmp_lt_i32 s0, 4
	s_cselect_b64 s[0:1], -1, 0
	s_and_b64 s[8:9], s[0:1], s[2:3]
	s_andn2_b64 vcc, exec, s[8:9]
	s_cbranch_vccnz .LBB0_1136
	s_load_dwordx2 s[2:3], s[90:91], 0x108
	s_waitcnt lgkmcnt(0)
	s_add_u32 s1, s2, 0xc000000
	s_addc_u32 s30, s3, 0
	s_add_u32 s31, s2, 0x1b00000
	s_addc_u32 s33, s3, 0
	s_add_u32 s34, s2, 0x32800000
	s_addc_u32 s35, s3, 0
	s_add_u32 s36, s2, 0x34b00000
	s_addc_u32 s37, s3, 0
	s_add_u32 s38, s2, 0x1d80000
	v_readlane_b32 s0, v254, 0
	s_addc_u32 s39, s3, 0
	s_andn2_b32 s0, s0, 63
	s_cmpk_lt_i32 s87, 0x200
	s_cselect_b64 s[4:5], -1, 0
	s_and_b32 s2, s87, 0xff
	v_mbcnt_lo_u32_b32 v8, -1, 0
	v_mbcnt_hi_u32_b32 v8, -1, v8
	s_add_i32 s28, s2, 16
	v_add_u32_e32 v0, s0, v8
	s_ashr_i32 s2, s87, 8
	s_cmpk_gt_i32 s87, 0x1ff
	v_readfirstlane_b32 s6, v0
	s_cbranch_scc1 .LBB0_1084
	v_lshlrev_b32_e32 v1, 4, v0
	v_add_u32_e32 v2, 0x2000, v1
	v_ashrrev_i32_e32 v3, 31, v2
	v_lshrrev_b32_e32 v3, 22, v3
	v_add_u32_e32 v3, v2, v3
	v_ashrrev_i32_e32 v9, 10, v3
	v_mul_i32_i24_e32 v3, 0x400, v9
	v_sub_u32_e32 v2, v2, v3
	v_lshrrev_b32_e32 v3, 4, v2
	v_bitop3_b32 v2, v3, v2, 32 bitop3:0x6c
	v_ashrrev_i32_e32 v3, 31, v2
	v_lshrrev_b32_e32 v3, 26, v3
	v_add_u32_e32 v3, v2, v3
	v_lshlrev_b32_e32 v4, 3, v9
	v_ashrrev_i32_e32 v10, 6, v3
	v_and_b32_e32 v4, -16, v4
	v_add_u32_e32 v4, v10, v4
	v_and_b32_e32 v5, 3, v10
	s_mov_b32 s3, 0xfffe0
	v_lshrrev_b32_e32 v6, 2, v4
	v_lshlrev_b32_e32 v7, 1, v4
	v_and_b32_e32 v3, 0xc0, v3
	v_and_or_b32 v5, v4, s3, v5
	v_and_b32_e32 v6, 4, v6
	v_and_b32_e32 v7, 24, v7
	v_sub_u32_e32 v2, v2, v3
	v_mov_b32_e32 v3, 1
	v_or3_b32 v5, v5, v6, v7
	v_lshlrev_b32_e32 v6, 5, v9
	v_ashrrev_i16_sdwa v2, v3, sext(v2) dst_sel:DWORD dst_unused:UNUSED_PAD src0_sel:DWORD src1_sel:BYTE_0
	v_and_b32_e32 v6, 32, v6
	v_bfe_i32 v11, v2, 0, 16
	v_add_lshl_u32 v2, v6, v11, 1
	v_lshl_add_u32 v144, v5, 12, v2
	v_lshl_add_u32 v146, v4, 11, v2
	v_bfe_i32 v2, v0, 27, 1
	v_lshrrev_b32_e32 v2, 22, v2
	v_add_u32_e32 v2, v1, v2
	v_and_b32_e32 v2, 0xfffffc00, v2
	v_sub_u32_e32 v1, v1, v2
	v_lshrrev_b32_e32 v2, 4, v1
	v_ashrrev_i32_e32 v4, 31, v0
	v_bitop3_b32 v1, v2, v1, 32 bitop3:0x6c
	v_lshrrev_b32_e32 v4, 26, v4
	v_ashrrev_i32_e32 v2, 31, v1
	v_add_u32_e32 v0, v0, v4
	v_lshrrev_b32_e32 v2, 26, v2
	v_ashrrev_i32_e32 v13, 6, v0
	v_add_u32_e32 v2, v1, v2
	v_lshlrev_b32_e32 v0, 3, v13
	v_ashrrev_i32_e32 v12, 6, v2
	v_and_b32_e32 v0, -16, v0
	v_add_u32_e32 v0, v12, v0
	v_and_b32_e32 v4, 3, v12
	v_lshrrev_b32_e32 v5, 2, v0
	v_lshlrev_b32_e32 v6, 1, v0
	v_and_b32_e32 v2, 0xc0, v2
	s_ashr_i32 s12, s6, 6
	v_and_or_b32 v4, v0, s3, v4
	v_and_b32_e32 v5, 4, v5
	v_and_b32_e32 v6, 24, v6
	v_sub_u32_e32 v1, v1, v2
	s_ashr_i32 s3, s2, 31
	s_ashr_i32 s13, s6, 8
	s_lshl_b32 s29, s12, 10
	v_or3_b32 v4, v4, v5, v6
	v_lshlrev_b32_e32 v5, 5, v13
	v_ashrrev_i16_sdwa v1, v3, sext(v1) dst_sel:DWORD dst_unused:UNUSED_PAD src0_sel:DWORD src1_sel:BYTE_0
	s_lshl_b32 s15, s28, 19
	s_lshl_b64 s[10:11], s[2:3], 20
	v_and_b32_e32 v5, 32, v5
	v_bfe_i32 v14, v1, 0, 16
	s_add_u32 s24, s31, s10
	v_add_lshl_u32 v1, v5, v14, 1
	s_addc_u32 s25, s33, s11
	s_add_i32 s3, s29, 0
	v_lshl_add_u32 v148, v4, 12, v1
	s_add_i32 m0, s3, 0x10000
	s_mul_i32 s14, s2, 0x8a00000
	global_load_lds_dwordx4 v148, s[24:25]
	s_add_i32 m0, s3, 0x12000
	s_mul_hi_i32 s7, s2, 0x8a00000
	s_add_u32 s14, s1, s14
	s_addc_u32 s7, s30, s7
	s_add_u32 s10, s24, 0x80000
	global_load_lds_dwordx4 v144, s[24:25]
	s_addc_u32 s11, s25, 0
	s_add_i32 m0, s3, 0x14000
	v_lshl_add_u32 v150, v0, 11, v1
	global_load_lds_dwordx4 v148, s[10:11]
	s_add_i32 m0, s3, 0x16000
	s_add_u32 s22, s14, s15
	s_addc_u32 s23, s7, 0
	s_add_i32 s40, s3, 0x2000
	global_load_lds_dwordx4 v144, s[10:11]
	s_mov_b32 m0, s3
	s_add_u32 s10, s22, 0x40000
	global_load_lds_dwordx4 v150, s[22:23]
	s_mov_b32 m0, s40
	s_addc_u32 s11, s23, 0
	s_add_i32 s41, s3, 0x4000
	global_load_lds_dwordx4 v146, s[22:23]
	s_mov_b32 m0, s41
	s_add_i32 s42, s3, 0x6000
	global_load_lds_dwordx4 v150, s[10:11]
	s_mov_b32 m0, s42
	v_mov_b32_e32 v149, 0
	global_load_lds_dwordx4 v146, s[10:11]
	v_mov_b32_e32 v145, v149
	v_mov_b32_e32 v151, v149
	v_mov_b32_e32 v147, v149
	s_cmp_eq_u32 s13, 1
	s_mov_b32 s7, 0
	v_lshl_add_u64 v[6:7], s[24:25], 0, v[148:149]
	v_lshl_add_u64 v[4:5], s[24:25], 0, v[144:145]
	v_lshl_add_u64 v[0:1], s[22:23], 0, v[150:151]
	s_cselect_b64 s[10:11], -1, 0
	s_cmp_lg_u32 s13, 1
	v_lshl_add_u64 v[2:3], s[22:23], 0, v[146:147]
	s_cbranch_scc1 .LBB0_1069
	s_barrier

; #define SEAM(k) do { if (IN(k) && IN((k) + 1)) xcd_barrier(bar, C.wave); } while (0)
; #define RUN(k, BODY) do { if (IN(k)) { unsigned char* ws = P.ws; LAUNDER_GPTR(ws); BODY } } while (0)
; __device__ __forceinline__ void phase_attention(const Params& P, const Ctx& C, int parts, int qset) {
;     ...
;             const int us = __builtin_amdgcn_readfirstlane((int)u);
;             int pq = -1, dq = -1;
;             if (us < 96) { const int k = us / 3, r = us - 3 * k; if (r == 0) pq = 63 - k; else dq = 2 * k + r - 1; } else pq = 127 - us;
; __global__ void __launch_bounds__(NWAVES * 64, 2) fwd_kernel(Params P) {
;     ...
;     RUN(3, PH3); SEAM(3);
.LBB0_1136:
	s_bitcmp1_b32 s101, 1
	s_cbranch_scc1 .Lmy_e7
	s_bitset1_b32 s101, 1
	s_cmpk_lg_i32 s68, 0x100
	s_cbranch_scc1 .Lmy_e7
	s_bitset1_b32 s101, 3
	v_readlane_b32 s99, v254, 10
	s_cmpk_lt_u32 s99, 160
	s_cbranch_scc1 .Lmy_e7
	s_and_b32 s100, s99, 31
	s_mul_i32 s100, s100, 3
	s_add_i32 s100, s100, 1
	s_bitset1_b32 s101, 0
	s_waitcnt vmcnt(0)
	s_barrier
	s_mov_b64 s[2:3], -1
	s_branch .LBB0_1192

; #define LAS __attribute__((address_space(3)))
; __device__ __forceinline__ unsigned xb_xcc_id() { return (unsigned)__builtin_amdgcn_s_getreg((3 << 11) | 20) & 0xFu; }
; __device__ __forceinline__ void phase_attention(const Params& P, const Ctx& C, int parts, int qset) {
;     unsigned* qc = (unsigned*)(P.ws + WS_CTL) + CW_QUEUE + qset * 512;
;     volatile LAS unsigned* slot = (volatile LAS unsigned*)(C.lds + MISC_OFF) + 16;
;     const bool fixed_ok = ((const float*)(P.ws + WS_PEB))[768] < 100.f;
;     const int x0 = (int)(xb_xcc_id() & 7u);
;     for (int i = 0; i < 8; ++i) { const int x = (x0 + i) & 7;
.LBB0_1194:
	v_readlane_b32 s2, v254, 8
	v_readlane_b32 s3, v254, 9
	s_cmp_lt_i32 s2, 6
	s_cselect_b64 s[0:1], -1, 0
	s_cmp_gt_i32 s3, 5
	s_cselect_b64 s[2:3], -1, 0
	s_and_b64 s[4:5], s[0:1], s[2:3]
	s_andn2_b64 vcc, exec, s[4:5]
	s_cbranch_vccnz .LBB0_1600
	s_load_dwordx2 s[58:59], s[90:91], 0x108
	v_mov_b32_e32 v0, 0x1d80000
	v_writelane_b32 v254, s4, 45
	s_mov_b32 s65, 0
	s_mov_b32 s67, s65
	s_waitcnt lgkmcnt(0)
	s_mov_b64 s[0:1], s[58:59]
	global_load_dword v0, v0, s[58:59] offset:3072
	s_load_dwordx2 s[0:1], s[90:91], 0x118
	v_writelane_b32 v254, s5, 46
	s_mov_b32 s4, 0x42c80000
	v_readlane_b32 s10, v254, 6
	v_readlane_b32 s11, v254, 7
	s_waitcnt lgkmcnt(0)
	s_bitcmp1_b32 s101, 0
	s_cbranch_scc0 .Lmy_e1
	s_mov_b32 s0, 1
	s_andn2_b32 s1, s1, 0x100
	s_or_b32 s1, s1, 0x200
.Lmy_e1:
	s_lshl_b32 s2, s0, 9
	s_ashr_i32 s3, s2, 31
	s_lshl_b64 s[2:3], s[2:3], 2
	s_add_u32 s0, s58, s2
	s_addc_u32 s2, s59, s3
	s_add_u32 s0, s0, 0x10000
	v_writelane_b32 v254, s0, 47
	s_addc_u32 s0, s2, 0
	v_writelane_b32 v254, s0, 48
	s_bitcmp1_b32 s1, 9
	s_cselect_b64 s[48:49], -1, 0
	s_bitcmp1_b32 s1, 8
	v_readlane_b32 s1, v254, 0
	s_cselect_b64 s[54:55], -1, 0
	s_cmp_lt_u32 s1, 64
	s_cselect_b64 s[86:87], -1, 0
	s_cmp_gt_u32 s1, 63
	s_cselect_b64 s[2:3], -1, 0
	s_mov_b32 s11, s65
	v_writelane_b32 v254, s2, 49
	s_lshl_b32 s0, s10, 14
	s_and_b32 s51, s1, 0xffffffc0
	v_writelane_b32 v254, s3, 50
	s_lshl_b64 s[2:3], s[10:11], 14
	s_add_i32 s33, s0, 0
	s_cmpk_lt_u32 s1, 0x880
	s_mul_i32 s5, s10, 0xffffc400
	s_cselect_b64 s[60:61], -1, 0
	s_lshl_b32 s6, s10, 9
	s_lshl_b32 s44, s10, 10
	s_add_i32 s1, 0, 0x20400
	s_add_i32 s82, s33, s5
	s_lshl_b32 s5, s10, 8
	s_add_i32 s11, s10, -8
	s_add_i32 s71, s6, 0
	v_writelane_b32 v254, s11, 51
	s_add_i32 s70, s1, s44
	s_add_i32 s76, s1, s5
	s_add_i32 s1, s71, 0x19100
	v_writelane_b32 v254, s1, 52
	s_add_i32 s1, s71, 0x1b100
	v_writelane_b32 v254, s1, 53
	s_add_i32 s1, s71, 0x1d100
	v_writelane_b32 v254, s1, 54
	s_add_i32 s1, s71, 0x1f100
	v_writelane_b32 v254, s1, 55
	s_add_i32 s1, s71, 0x1c100
	v_writelane_b32 v254, s1, 56
	s_add_i32 s1, s71, 0x10100
	v_writelane_b32 v254, s1, 57
	s_add_i32 s1, s71, 0x12100
	v_writelane_b32 v254, s1, 58
	s_add_i32 s1, s71, 0x14100
	v_writelane_b32 v254, s1, 59
	s_add_i32 s1, s71, 0x16100
	v_writelane_b32 v254, s1, 60
	s_add_i32 s1, s71, 0x18100
	v_writelane_b32 v254, s1, 61
	s_add_i32 s1, s71, 0x1a100
	v_writelane_b32 v254, s1, 62
	s_add_i32 s1, s71, 0x1e100
	v_writelane_b32 v254, s1, 63
	s_add_i32 s1, s71, 0x1c000
	v_writelane_b32 v255, s1, 0
	s_add_i32 s1, s71, 0x11000
	v_writelane_b32 v255, s1, 1
	s_add_i32 s1, s71, 0x13000
	v_writelane_b32 v255, s1, 2
	s_add_i32 s1, s71, 0x15000
	v_writelane_b32 v255, s1, 3
	s_add_i32 s1, s71, 0x17000
	v_writelane_b32 v255, s1, 4
	s_add_i32 s1, s71, 0x19000
	v_writelane_b32 v255, s1, 5
	s_add_i32 s1, s71, 0x1b000
	v_writelane_b32 v255, s1, 6
	s_add_i32 s1, s71, 0x1d000
	v_writelane_b32 v255, s1, 7
	s_add_i32 s1, s71, 0x1f000
	v_writelane_b32 v255, s1, 8
	s_add_i32 s1, s71, 0x10000
	v_writelane_b32 v255, s1, 9
	s_add_i32 s1, s71, 0x12000
	v_writelane_b32 v255, s1, 10
	s_add_i32 s1, s71, 0x14000
	v_writelane_b32 v255, s1, 11
	s_add_i32 s1, s71, 0x16000
	v_writelane_b32 v255, s1, 12
	s_add_i32 s1, s71, 0x18000
	v_writelane_b32 v255, s1, 13
	s_add_i32 s1, s71, 0x1a000
	v_writelane_b32 v255, s1, 14
	s_add_i32 s1, s71, 0x1e000
	s_lshl_b32 s9, s10, 13
	v_writelane_b32 v255, s1, 15
	s_waitcnt vmcnt(0)
	v_cmp_ngt_f32_e64 s[4:5], s4, v0
	s_add_i32 s72, s9, 0
	s_add_i32 s1, s72, 0x10000
	v_writelane_b32 v255, s4, 16
	s_addk_i32 s0, 0xc000
	v_writelane_b32 v254, s1, 27
	v_writelane_b32 v255, s5, 17
	v_writelane_b32 v255, s0, 18
	s_mov_b32 s0, s10
	s_lshl_b32 s7, s10, 2
	s_lshl_b32 s8, s10, 1
	s_lshl_b32 s66, s10, 4
	v_writelane_b32 v254, s0, 6
	s_and_b32 s6, s7, 0xffffff8
	s_and_b32 s7, s8, 2
	s_and_b32 s73, s66, 48
	s_and_b32 s68, s66, 0x3fffffc0
	s_add_i32 s77, s71, 0x22a00
	s_add_i32 s78, s71, 0x11100
	s_add_i32 s79, s71, 0x13100
	s_add_i32 s80, s71, 0x15100
	s_add_i32 s81, s71, 0x17100
	v_writelane_b32 v254, s1, 7
	s_lshl_b32 s0, s10, 6
	v_writelane_b32 v255, s0, 19
	s_add_u32 s0, s68, 0xb800000
	v_writelane_b32 v255, s0, 20
	s_addc_u32 s0, 0, 0
	v_writelane_b32 v255, s0, 21
	s_add_u32 s0, s66, 0xb000000
	v_writelane_b32 v255, s0, 22
	s_addc_u32 s0, 0, 0
	s_add_i32 s1, 0, 0x22400
	v_writelane_b32 v255, s0, 23
	s_add_i32 s0, 0, 0x20180
	v_writelane_b32 v254, s1, 28
	s_add_i32 s1, 0, 0x22800
	v_writelane_b32 v255, s1, 24
	v_writelane_b32 v254, s0, 35
	v_mov_b32_e32 v218, s0
	s_lshl_b64 s[0:1], s[2:3], 2
	v_writelane_b32 v255, s0, 25
	s_getreg_b32 s12, hwreg(HW_REG_XCC_ID, 0, 4)
	s_bitcmp1_b32 s101, 0
	s_cbranch_scc0 .Lmy_e3
	v_readlane_b32 s12, v254, 10
	s_lshr_b32 s12, s12, 5
.Lmy_e3:
	v_mbcnt_lo_u32_b32 v0, -1, 0
	v_writelane_b32 v255, s1, 26
	s_lshl_b32 s0, s6, 1
	v_writelane_b32 v255, s0, 27
	v_mbcnt_hi_u32_b32 v220, -1, v0
	v_and_b32_e32 v0, 64, v220
	v_writelane_b32 v255, s1, 28
	s_lshl_b32 s0, s7, 1
	v_writelane_b32 v255, s0, 29
	s_load_dwordx8 s[4:11], s[90:91], 0x20
	s_mov_b32 s69, s65
	v_writelane_b32 v255, s1, 30
	v_writelane_b32 v255, s12, 31
	v_writelane_b32 v255, s58, 32
	s_waitcnt lgkmcnt(0)
	v_writelane_b32 v254, s4, 37
	v_cndmask_b32_e64 v209, 0, 1, s[86:87]
	v_writelane_b32 v255, s59, 33
	v_writelane_b32 v255, s48, 34
	v_writelane_b32 v254, s5, 38
	v_writelane_b32 v254, s6, 39
	v_writelane_b32 v255, s49, 35
	v_writelane_b32 v255, s54, 36
	v_writelane_b32 v254, s7, 40
	v_writelane_b32 v254, s8, 41
	v_writelane_b32 v255, s55, 37
	v_writelane_b32 v255, s60, 38
	v_writelane_b32 v254, s9, 42
	v_writelane_b32 v254, s10, 43
	v_writelane_b32 v255, s61, 39
	v_writelane_b32 v255, s82, 40
	v_writelane_b32 v255, s70, 41
	v_writelane_b32 v255, s71, 42
	v_writelane_b32 v255, s72, 43
	v_writelane_b32 v255, s73, 44
	v_writelane_b32 v255, s76, 45
	v_writelane_b32 v255, s77, 46
	v_writelane_b32 v255, s78, 47
	v_writelane_b32 v255, s79, 48
	v_writelane_b32 v255, s80, 49
	v_writelane_b32 v255, s81, 50
	v_writelane_b32 v255, s51, 51
	v_mov_b32_e32 v1, 0
	s_mov_b32 s50, 0xff800000
	s_movk_i32 s46, 0xffe0
	s_mov_b32 s45, 0xc000
	v_mov_b32_e32 v219, 0xff800000
	v_xor_b32_e32 v221, 32, v220
	v_add_u32_e32 v222, 64, v0
	v_xor_b32_e32 v223, 4, v220
	v_mov_b32_e32 v226, 0x3f803f80
	s_mov_b32 s47, 0xe000
	s_mov_b32 s62, 0xf000
	s_mov_b32 s63, 0xf149f2ca
	s_mov_b32 s1, 0xefa18f08
	s_mov_b32 s0, 0x41000000
	s_mov_b32 s3, 0
	v_writelane_b32 v254, s11, 44
	v_writelane_b32 v255, s33, 52
	s_branch .LBB0_1197

; __device__ __forceinline__ int fresh_lane() { int l; asm volatile("v_mbcnt_lo_u32_b32 %0, -1, 0\n\tv_mbcnt_hi_u32_b32 %0, -1, %0" : "=v"(l)); return l; }
; __device__ __forceinline__ void phase_attention(const Params& P, const Ctx& C, int parts, int qset) {
;     ...
;         for (;;) {
;             __syncthreads();
;             if (C.wave == 0 && fresh_lane() == 0) *slot = __hip_atomic_fetch_add(qc + 64 * x, 1u, __ATOMIC_RELAXED, __HIP_MEMORY_SCOPE_AGENT);
;             __syncthreads();
;             const unsigned u = *slot;
;             if (u >= 128u) break;
.LBB0_1200:
	s_bitcmp1_b32 s101, 0
	s_cbranch_scc1 .LBB0_1599
	s_mov_b64 s[2:3], 0

; __device__ __forceinline__ int fresh_lane() { int l; asm volatile("v_mbcnt_lo_u32_b32 %0, -1, 0\n\tv_mbcnt_hi_u32_b32 %0, -1, %0" : "=v"(l)); return l; }
; __device__ __forceinline__ void phase_attention(const Params& P, const Ctx& C, int parts, int qset) {
;     ...
;             if (C.wave == 0 && fresh_lane() == 0) *slot = __hip_atomic_fetch_add(qc + 64 * x, 1u, __ATOMIC_RELAXED, __HIP_MEMORY_SCOPE_AGENT);
;             __syncthreads();
;             const unsigned u = *slot;
.LBB0_1206:
	s_or_b64 exec, exec, s[4:5]
	s_waitcnt vmcnt(0)
	v_readfirstlane_b32 s4, v2
	s_bitcmp1_b32 s101, 0
	s_cselect_b32 s4, s100, s4
	s_nop 1
	v_add_u32_e32 v0, s4, v0
	v_readlane_b32 s4, v254, 35
	s_nop 1
	v_mov_b32_e32 v2, s4
	ds_write_b32 v2, v0

; __device__ __forceinline__ void phase_attention(const Params& P, const Ctx& C, int parts, int qset) {
;     ...
;             const int us = __builtin_amdgcn_readfirstlane((int)u);
;             int pq = -1, dq = -1;
;             if (us < 96) { const int k = us / 3, r = us - 3 * k; if (r == 0) pq = 63 - k; else dq = 2 * k + r - 1; } else pq = 127 - us;
;             if (pq >= 0) { if (parts & 1) { if (fixed_ok) attn_prompt_unit<true>(P, C, x, pq); else attn_prompt_unit<false>(P, C, x, pq); } }
;             else { if (parts & 2) attn_decode_unit(P, C, x * 64 + dq); }
.LBB0_1215:
	s_bitcmp1_b32 s101, 0
	s_cbranch_scc1 .Lmy_e8
	s_bitcmp1_b32 s101, 3
	s_cbranch_scc0 .Lmy_e8
	v_readlane_b32 s99, v254, 13
	s_cmpk_lt_u32 s99, 320
	s_cbranch_scc1 .Lmy_e8
	s_bitcmp0_b32 s4, 0
	s_cbranch_scc1 .LBB0_1200

; #define SEAM(k) do { if (IN(k) && IN((k) + 1)) xcd_barrier(bar, C.wave); } while (0)
; #define PH5 { phase_attention(P, C, (P.pad >> 8) & 3, P.li); }
; #define RUN(k, BODY) do { if (IN(k)) { unsigned char* ws = P.ws; LAUNDER_GPTR(ws); BODY } } while (0)
; __global__ void __launch_bounds__(NWAVES * 64, 2) fwd_kernel(Params P) {
;     ...
;     RUN(3, PH3); SEAM(3);
;     RUN(4, PH4);
;     RUN(5, PH5); SEAM(5);
.LBB0_1600:
	s_bitcmp1_b32 s101, 0
	s_cbranch_scc0 .Lmy_e6
	s_bitset0_b32 s101, 0
	s_waitcnt lgkmcnt(0)
	s_mov_b64 s[8:9], -1
	s_branch .LBB0_1136
